# EpiRes epilogue with f32 residual inputs (out-proj phase): old values prefetched 4 segments ahead
# speedup vs baseline: 1.0699x; 1.0032x over previous
.LBB0_481:
	v_lshl_add_u32 v172, s76, 8, v194
	v_ashrrev_i32_e32 v173, 31, v172
	v_lshlrev_b64 v[144:145], 12, v[172:173]
	v_cndmask_b32_e64 v146, 0, 1, s[20:21]
	v_cmp_ne_u32_e64 s[6:7], 1, v146
	s_andn2_b64 vcc, exec, s[20:21]
	v_lshl_add_u64 v[178:179], s[48:49], 0, v[144:145]
	v_cmp_gt_i32_e64 s[8:9], s70, v172
	v_subrev_u32_e32 v152, s70, v172
	s_cbranch_vccnz .LBB0_483
	v_lshlrev_b64 v[144:145], 12, v[152:153]
	v_lshl_add_u64 v[144:145], s[28:29], 0, v[144:145]
	v_cndmask_b32_e64 v145, v145, v179, s[8:9]
	v_cndmask_b32_e64 v144, v144, v178, s[8:9]
	v_lshl_add_u64 v[148:149], v[170:171], 2, v[144:145]
	v_lshlrev_b32_e32 v250, 12, v172
	v_lshl_add_u32 v250, v170, 2, v250
	global_load_dwordx4 v[198:201], v250, s[48:49] offset:16
	global_load_dwordx4 v[202:205], v250, s[48:49]
	v_add_u32_e32 v251, 0x200, v250
	global_load_dwordx4 v[206:209], v251, s[48:49] offset:16
	global_load_dwordx4 v[210:213], v251, s[48:49]
	v_add_u32_e32 v251, 0x10000, v250
	global_load_dwordx4 v[214:217], v251, s[48:49] offset:16
	global_load_dwordx4 v[218:221], v251, s[48:49]
	v_add_u32_e32 v251, 0x10200, v250
	global_load_dwordx4 v[222:225], v251, s[48:49] offset:16
	global_load_dwordx4 v[238:241], v251, s[48:49]
	s_waitcnt vmcnt(6)
	v_mov_b32_e32 v144, v198
	v_mov_b32_e32 v145, v199
	v_mov_b32_e32 v146, v200
	v_mov_b32_e32 v147, v201
	v_mov_b32_e32 v148, v202
	v_mov_b32_e32 v149, v203
	v_mov_b32_e32 v150, v204
	v_mov_b32_e32 v151, v205
	v_add_u32_e32 v251, 0x20000, v250
	global_load_dwordx4 v[198:201], v251, s[48:49] offset:16
	global_load_dwordx4 v[202:205], v251, s[48:49]
	s_mov_b64 s[8:9], 0
	s_branch .LBB0_484

.LBB0_486:
	v_pk_add_f32 v[142:143], v[142:143], v[70:71]
	v_pk_add_f32 v[140:141], v[140:141], v[68:69]
	v_pk_add_f32 v[138:139], v[138:139], v[66:67]
	v_pk_add_f32 v[136:137], v[136:137], v[64:65]
	v_pk_add_f32 v[150:151], v[142:143], v[150:151]
	v_pk_add_f32 v[148:149], v[140:141], v[148:149]
	v_pk_add_f32 v[146:147], v[138:139], v[146:147]
	v_pk_add_f32 v[180:181], v[136:137], v[144:145]
	v_or_b32_e32 v144, 0x80, v170
	v_cvt_pk_bf16_f32 v136, v148, v149
	v_cvt_pk_bf16_f32 v137, v150, v151
	v_cvt_pk_bf16_f32 v138, v180, v181
	v_cvt_pk_bf16_f32 v139, v146, v147
	s_and_b64 vcc, exec, s[6:7]
	v_ashrrev_i32_e32 v145, 31, v144
	global_store_dwordx4 v[176:177], v[136:139], off
	s_cbranch_vccnz .LBB0_493
	s_nop 0
	v_lshlrev_b64 v[136:137], 12, v[152:153]
	v_lshl_add_u64 v[136:137], s[28:29], 0, v[136:137]
	v_cmp_gt_i32_e32 vcc, s70, v172
	s_nop 1
	v_cndmask_b32_e32 v137, v137, v179, vcc
	v_cndmask_b32_e32 v136, v136, v178, vcc
	v_lshl_add_u64 v[140:141], v[170:171], 2, v[136:137]
	s_waitcnt vmcnt(5)
	v_mov_b32_e32 v136, v206
	v_mov_b32_e32 v137, v207
	v_mov_b32_e32 v138, v208
	v_mov_b32_e32 v139, v209
	v_mov_b32_e32 v140, v210
	v_mov_b32_e32 v141, v211
	v_mov_b32_e32 v142, v212
	v_mov_b32_e32 v143, v213
	v_add_u32_e32 v251, 0x20200, v250
	global_load_dwordx4 v[206:209], v251, s[48:49] offset:16
	global_load_dwordx4 v[210:213], v251, s[48:49]
	s_cbranch_execnz .LBB0_489

.LBB0_491:
	s_or_b64 exec, exec, s[8:9]
	v_or_b32_e32 v136, 16, v172
	v_ashrrev_i32_e32 v137, 31, v136
	s_waitcnt lgkmcnt(0)
	v_lshlrev_b64 v[128:129], 12, v[136:137]
	s_and_b64 vcc, exec, s[6:7]
	v_lshl_add_u64 v[138:139], s[48:49], 0, v[128:129]
	v_cmp_gt_i32_e64 s[8:9], s70, v136
	v_subrev_u32_e32 v152, s70, v136
	s_cbranch_vccnz .LBB0_494
	v_lshlrev_b64 v[128:129], 12, v[152:153]
	v_lshl_add_u64 v[128:129], s[28:29], 0, v[128:129]
	v_cndmask_b32_e64 v129, v129, v139, s[8:9]
	v_cndmask_b32_e64 v128, v128, v138, s[8:9]
	v_lshl_add_u64 v[132:133], v[170:171], 2, v[128:129]
	s_waitcnt vmcnt(7)
	v_mov_b32_e32 v128, v214
	v_mov_b32_e32 v129, v215
	v_mov_b32_e32 v130, v216
	v_mov_b32_e32 v131, v217
	v_mov_b32_e32 v132, v218
	v_mov_b32_e32 v133, v219
	v_mov_b32_e32 v134, v220
	v_mov_b32_e32 v135, v221
	v_add_u32_e32 v251, 0x30000, v250
	global_load_dwordx4 v[214:217], v251, s[48:49] offset:16
	global_load_dwordx4 v[218:221], v251, s[48:49]
	s_mov_b64 s[8:9], 0
	s_branch .LBB0_495

.LBB0_497:
	v_pk_add_f32 v[126:127], v[126:127], v[70:71]
	v_pk_add_f32 v[124:125], v[124:125], v[68:69]
	v_pk_add_f32 v[122:123], v[122:123], v[66:67]
	v_pk_add_f32 v[120:121], v[120:121], v[64:65]
	v_pk_add_f32 v[134:135], v[126:127], v[134:135]
	v_pk_add_f32 v[132:133], v[124:125], v[132:133]
	v_pk_add_f32 v[130:131], v[122:123], v[130:131]
	v_pk_add_f32 v[142:143], v[120:121], v[128:129]
	v_cvt_pk_bf16_f32 v120, v132, v133
	v_cvt_pk_bf16_f32 v121, v134, v135
	v_cvt_pk_bf16_f32 v122, v142, v143
	v_cvt_pk_bf16_f32 v123, v130, v131
	s_and_b64 vcc, exec, s[6:7]
	global_store_dwordx4 v[146:147], v[120:123], off
	s_cbranch_vccnz .LBB0_504
	s_nop 0
	v_lshlrev_b64 v[120:121], 12, v[152:153]
	v_lshl_add_u64 v[120:121], s[28:29], 0, v[120:121]
	v_cmp_gt_i32_e32 vcc, s70, v136
	s_nop 1
	v_cndmask_b32_e32 v121, v121, v139, vcc
	v_cndmask_b32_e32 v120, v120, v138, vcc
	v_lshl_add_u64 v[124:125], v[144:145], 2, v[120:121]
	s_waitcnt vmcnt(8)
	v_mov_b32_e32 v120, v222
	v_mov_b32_e32 v121, v223
	v_mov_b32_e32 v122, v224
	v_mov_b32_e32 v123, v225
	v_mov_b32_e32 v124, v238
	v_mov_b32_e32 v125, v239
	v_mov_b32_e32 v126, v240
	v_mov_b32_e32 v127, v241
	v_add_u32_e32 v251, 0x30200, v250
	global_load_dwordx4 v[222:225], v251, s[48:49] offset:16
	global_load_dwordx4 v[238:241], v251, s[48:49]
	v_lshl_add_u64 v[128:129], v[144:145], 1, v[140:141]
	s_cbranch_execnz .LBB0_500

.LBB0_502:
	s_or_b64 exec, exec, s[8:9]
	v_or_b32_e32 v120, 32, v172
	v_ashrrev_i32_e32 v121, 31, v120
	s_waitcnt lgkmcnt(0)
	v_lshlrev_b64 v[112:113], 12, v[120:121]
	s_and_b64 vcc, exec, s[6:7]
	v_lshl_add_u64 v[122:123], s[48:49], 0, v[112:113]
	v_cmp_gt_i32_e64 s[8:9], s70, v120
	v_subrev_u32_e32 v152, s70, v120
	s_cbranch_vccnz .LBB0_505
	v_lshlrev_b64 v[112:113], 12, v[152:153]
	v_lshl_add_u64 v[112:113], s[28:29], 0, v[112:113]
	v_cndmask_b32_e64 v113, v113, v123, s[8:9]
	v_cndmask_b32_e64 v112, v112, v122, s[8:9]
	v_lshl_add_u64 v[116:117], v[170:171], 2, v[112:113]
	s_waitcnt vmcnt(10)
	v_mov_b32_e32 v112, v198
	v_mov_b32_e32 v113, v199
	v_mov_b32_e32 v114, v200
	v_mov_b32_e32 v115, v201
	v_mov_b32_e32 v116, v202
	v_mov_b32_e32 v117, v203
	v_mov_b32_e32 v118, v204
	v_mov_b32_e32 v119, v205
	v_add_u32_e32 v251, 0x80000, v250
	global_load_dwordx4 v[198:201], v251, s[48:49] offset:16
	global_load_dwordx4 v[202:205], v251, s[48:49]
	s_mov_b64 s[8:9], 0
	s_branch .LBB0_506

.LBB0_508:
	v_pk_add_f32 v[110:111], v[110:111], v[70:71]
	v_pk_add_f32 v[108:109], v[108:109], v[68:69]
	v_pk_add_f32 v[106:107], v[106:107], v[66:67]
	v_pk_add_f32 v[104:105], v[104:105], v[64:65]
	v_pk_add_f32 v[118:119], v[110:111], v[118:119]
	v_pk_add_f32 v[116:117], v[108:109], v[116:117]
	v_pk_add_f32 v[114:115], v[106:107], v[114:115]
	v_pk_add_f32 v[126:127], v[104:105], v[112:113]
	v_cvt_pk_bf16_f32 v104, v116, v117
	v_cvt_pk_bf16_f32 v105, v118, v119
	v_cvt_pk_bf16_f32 v106, v126, v127
	v_cvt_pk_bf16_f32 v107, v114, v115
	s_and_b64 vcc, exec, s[6:7]
	global_store_dwordx4 v[128:129], v[104:107], off
	s_cbranch_vccnz .LBB0_515
	s_nop 0
	v_lshlrev_b64 v[104:105], 12, v[152:153]
	v_lshl_add_u64 v[104:105], s[28:29], 0, v[104:105]
	v_cmp_gt_i32_e32 vcc, s70, v120
	s_nop 1
	v_cndmask_b32_e32 v105, v105, v123, vcc
	v_cndmask_b32_e32 v104, v104, v122, vcc
	v_lshl_add_u64 v[108:109], v[144:145], 2, v[104:105]
	s_waitcnt vmcnt(10)
	v_mov_b32_e32 v104, v206
	v_mov_b32_e32 v105, v207
	v_mov_b32_e32 v106, v208
	v_mov_b32_e32 v107, v209
	v_mov_b32_e32 v108, v210
	v_mov_b32_e32 v109, v211
	v_mov_b32_e32 v110, v212
	v_mov_b32_e32 v111, v213
	v_add_u32_e32 v251, 0x80200, v250
	global_load_dwordx4 v[206:209], v251, s[48:49] offset:16
	global_load_dwordx4 v[210:213], v251, s[48:49]
	v_lshl_add_u64 v[112:113], v[144:145], 1, v[124:125]
	s_cbranch_execnz .LBB0_511

.LBB0_513:
	s_or_b64 exec, exec, s[8:9]
	v_or_b32_e32 v104, 48, v172
	v_ashrrev_i32_e32 v105, 31, v104
	s_waitcnt lgkmcnt(0)
	v_lshlrev_b64 v[96:97], 12, v[104:105]
	s_and_b64 vcc, exec, s[6:7]
	v_lshl_add_u64 v[106:107], s[48:49], 0, v[96:97]
	v_cmp_gt_i32_e64 s[8:9], s70, v104
	v_subrev_u32_e32 v152, s70, v104
	s_cbranch_vccnz .LBB0_516
	v_lshlrev_b64 v[96:97], 12, v[152:153]
	v_lshl_add_u64 v[96:97], s[28:29], 0, v[96:97]
	v_cndmask_b32_e64 v97, v97, v107, s[8:9]
	v_cndmask_b32_e64 v96, v96, v106, s[8:9]
	v_lshl_add_u64 v[100:101], v[170:171], 2, v[96:97]
	s_waitcnt vmcnt(10)
	v_mov_b32_e32 v96, v214
	v_mov_b32_e32 v97, v215
	v_mov_b32_e32 v98, v216
	v_mov_b32_e32 v99, v217
	v_mov_b32_e32 v100, v218
	v_mov_b32_e32 v101, v219
	v_mov_b32_e32 v102, v220
	v_mov_b32_e32 v103, v221
	v_add_u32_e32 v251, 0x90000, v250
	global_load_dwordx4 v[214:217], v251, s[48:49] offset:16
	global_load_dwordx4 v[218:221], v251, s[48:49]
	s_mov_b64 s[8:9], 0
	s_branch .LBB0_517

.LBB0_519:
	v_pk_add_f32 v[94:95], v[94:95], v[70:71]
	v_pk_add_f32 v[92:93], v[92:93], v[68:69]
	v_pk_add_f32 v[90:91], v[90:91], v[66:67]
	v_pk_add_f32 v[88:89], v[88:89], v[64:65]
	v_pk_add_f32 v[102:103], v[94:95], v[102:103]
	v_pk_add_f32 v[100:101], v[92:93], v[100:101]
	v_pk_add_f32 v[98:99], v[90:91], v[98:99]
	v_pk_add_f32 v[110:111], v[88:89], v[96:97]
	v_cvt_pk_bf16_f32 v88, v100, v101
	v_cvt_pk_bf16_f32 v89, v102, v103
	v_cvt_pk_bf16_f32 v90, v110, v111
	v_cvt_pk_bf16_f32 v91, v98, v99
	s_and_b64 vcc, exec, s[6:7]
	global_store_dwordx4 v[112:113], v[88:91], off
	s_cbranch_vccnz .LBB0_526
	s_nop 0
	v_lshlrev_b64 v[88:89], 12, v[152:153]
	v_lshl_add_u64 v[88:89], s[28:29], 0, v[88:89]
	v_cmp_gt_i32_e32 vcc, s70, v104
	s_nop 1
	v_cndmask_b32_e32 v89, v89, v107, vcc
	v_cndmask_b32_e32 v88, v88, v106, vcc
	v_lshl_add_u64 v[92:93], v[144:145], 2, v[88:89]
	s_waitcnt vmcnt(10)
	v_mov_b32_e32 v88, v222
	v_mov_b32_e32 v89, v223
	v_mov_b32_e32 v90, v224
	v_mov_b32_e32 v91, v225
	v_mov_b32_e32 v92, v238
	v_mov_b32_e32 v93, v239
	v_mov_b32_e32 v94, v240
	v_mov_b32_e32 v95, v241
	v_add_u32_e32 v251, 0x90200, v250
	global_load_dwordx4 v[222:225], v251, s[48:49] offset:16
	global_load_dwordx4 v[238:241], v251, s[48:49]
	v_lshl_add_u64 v[96:97], v[144:145], 1, v[108:109]
	s_cbranch_execnz .LBB0_522

.LBB0_524:
	s_or_b64 exec, exec, s[8:9]
	v_add_u32_e32 v88, 0x80, v172
	v_ashrrev_i32_e32 v89, 31, v88
	s_waitcnt lgkmcnt(0)
	v_lshlrev_b64 v[80:81], 12, v[88:89]
	s_and_b64 vcc, exec, s[6:7]
	v_lshl_add_u64 v[90:91], s[48:49], 0, v[80:81]
	v_cmp_gt_i32_e64 s[8:9], s70, v88
	v_subrev_u32_e32 v152, s70, v88
	s_cbranch_vccnz .LBB0_527
	v_lshlrev_b64 v[80:81], 12, v[152:153]
	v_lshl_add_u64 v[80:81], s[28:29], 0, v[80:81]
	v_cndmask_b32_e64 v81, v81, v91, s[8:9]
	v_cndmask_b32_e64 v80, v80, v90, s[8:9]
	v_lshl_add_u64 v[84:85], v[170:171], 2, v[80:81]
	s_waitcnt vmcnt(10)
	v_mov_b32_e32 v80, v198
	v_mov_b32_e32 v81, v199
	v_mov_b32_e32 v82, v200
	v_mov_b32_e32 v83, v201
	v_mov_b32_e32 v84, v202
	v_mov_b32_e32 v85, v203
	v_mov_b32_e32 v86, v204
	v_mov_b32_e32 v87, v205
	v_add_u32_e32 v251, 0xa0000, v250
	global_load_dwordx4 v[198:201], v251, s[48:49] offset:16
	global_load_dwordx4 v[202:205], v251, s[48:49]
	s_mov_b64 s[8:9], 0
	s_branch .LBB0_528

.LBB0_530:
	v_pk_add_f32 v[78:79], v[78:79], v[70:71]
	v_pk_add_f32 v[76:77], v[76:77], v[68:69]
	v_pk_add_f32 v[74:75], v[74:75], v[66:67]
	v_pk_add_f32 v[72:73], v[72:73], v[64:65]
	v_pk_add_f32 v[86:87], v[78:79], v[86:87]
	v_pk_add_f32 v[84:85], v[76:77], v[84:85]
	v_pk_add_f32 v[82:83], v[74:75], v[82:83]
	v_pk_add_f32 v[94:95], v[72:73], v[80:81]
	v_cvt_pk_bf16_f32 v72, v84, v85
	v_cvt_pk_bf16_f32 v73, v86, v87
	v_cvt_pk_bf16_f32 v74, v94, v95
	v_cvt_pk_bf16_f32 v75, v82, v83
	s_and_b64 vcc, exec, s[6:7]
	global_store_dwordx4 v[96:97], v[72:75], off
	s_cbranch_vccnz .LBB0_537
	s_nop 0
	v_lshlrev_b64 v[72:73], 12, v[152:153]
	v_lshl_add_u64 v[72:73], s[28:29], 0, v[72:73]
	v_cmp_gt_i32_e32 vcc, s70, v88
	s_nop 1
	v_cndmask_b32_e32 v73, v73, v91, vcc
	v_cndmask_b32_e32 v72, v72, v90, vcc
	v_lshl_add_u64 v[76:77], v[144:145], 2, v[72:73]
	s_waitcnt vmcnt(10)
	v_mov_b32_e32 v72, v206
	v_mov_b32_e32 v73, v207
	v_mov_b32_e32 v74, v208
	v_mov_b32_e32 v75, v209
	v_mov_b32_e32 v76, v210
	v_mov_b32_e32 v77, v211
	v_mov_b32_e32 v78, v212
	v_mov_b32_e32 v79, v213
	v_add_u32_e32 v251, 0xa0200, v250
	global_load_dwordx4 v[206:209], v251, s[48:49] offset:16
	global_load_dwordx4 v[210:213], v251, s[48:49]
	v_lshl_add_u64 v[80:81], v[144:145], 1, v[92:93]
	s_cbranch_execnz .LBB0_533

.LBB0_535:
	s_or_b64 exec, exec, s[8:9]
	v_add_u32_e32 v72, 0x90, v172
	v_ashrrev_i32_e32 v73, 31, v72
	s_waitcnt lgkmcnt(0)
	v_lshlrev_b64 v[48:49], 12, v[72:73]
	s_and_b64 vcc, exec, s[6:7]
	v_lshl_add_u64 v[74:75], s[48:49], 0, v[48:49]
	v_cmp_gt_i32_e64 s[8:9], s70, v72
	v_subrev_u32_e32 v152, s70, v72
	s_cbranch_vccnz .LBB0_538
	v_lshlrev_b64 v[48:49], 12, v[152:153]
	v_lshl_add_u64 v[48:49], s[28:29], 0, v[48:49]
	v_cndmask_b32_e64 v49, v49, v75, s[8:9]
	v_cndmask_b32_e64 v48, v48, v74, s[8:9]
	v_lshl_add_u64 v[52:53], v[170:171], 2, v[48:49]
	s_waitcnt vmcnt(10)
	v_mov_b32_e32 v48, v214
	v_mov_b32_e32 v49, v215
	v_mov_b32_e32 v50, v216
	v_mov_b32_e32 v51, v217
	v_mov_b32_e32 v52, v218
	v_mov_b32_e32 v53, v219
	v_mov_b32_e32 v54, v220
	v_mov_b32_e32 v55, v221
	v_add_u32_e32 v251, 0xb0000, v250
	global_load_dwordx4 v[214:217], v251, s[48:49] offset:16
	global_load_dwordx4 v[218:221], v251, s[48:49]
	s_mov_b64 s[8:9], 0
	s_branch .LBB0_539

.LBB0_541:
	v_pk_add_f32 v[46:47], v[46:47], v[70:71]
	v_pk_add_f32 v[44:45], v[44:45], v[68:69]
	v_pk_add_f32 v[42:43], v[42:43], v[66:67]
	v_pk_add_f32 v[40:41], v[40:41], v[64:65]
	v_pk_add_f32 v[54:55], v[46:47], v[54:55]
	v_pk_add_f32 v[52:53], v[44:45], v[52:53]
	v_pk_add_f32 v[50:51], v[42:43], v[50:51]
	v_pk_add_f32 v[78:79], v[40:41], v[48:49]
	v_cvt_pk_bf16_f32 v40, v52, v53
	v_cvt_pk_bf16_f32 v41, v54, v55
	v_cvt_pk_bf16_f32 v42, v78, v79
	v_cvt_pk_bf16_f32 v43, v50, v51
	s_and_b64 vcc, exec, s[6:7]
	global_store_dwordx4 v[80:81], v[40:43], off
	s_cbranch_vccnz .LBB0_548
	s_nop 0
	v_lshlrev_b64 v[40:41], 12, v[152:153]
	v_lshl_add_u64 v[40:41], s[28:29], 0, v[40:41]
	v_cmp_gt_i32_e32 vcc, s70, v72
	s_nop 1
	v_cndmask_b32_e32 v41, v41, v75, vcc
	v_cndmask_b32_e32 v40, v40, v74, vcc
	v_lshl_add_u64 v[44:45], v[144:145], 2, v[40:41]
	s_waitcnt vmcnt(10)
	v_mov_b32_e32 v40, v222
	v_mov_b32_e32 v41, v223
	v_mov_b32_e32 v42, v224
	v_mov_b32_e32 v43, v225
	v_mov_b32_e32 v44, v238
	v_mov_b32_e32 v45, v239
	v_mov_b32_e32 v46, v240
	v_mov_b32_e32 v47, v241
	v_add_u32_e32 v251, 0xb0200, v250
	global_load_dwordx4 v[222:225], v251, s[48:49] offset:16
	global_load_dwordx4 v[238:241], v251, s[48:49]
	v_lshl_add_u64 v[48:49], v[144:145], 1, v[76:77]
	s_cbranch_execnz .LBB0_544

.LBB0_546:
	s_or_b64 exec, exec, s[8:9]
	v_add_u32_e32 v40, 0xa0, v172
	v_ashrrev_i32_e32 v41, 31, v40
	s_waitcnt lgkmcnt(0)
	v_lshlrev_b64 v[32:33], 12, v[40:41]
	s_and_b64 vcc, exec, s[6:7]
	v_lshl_add_u64 v[42:43], s[48:49], 0, v[32:33]
	v_cmp_gt_i32_e64 s[8:9], s70, v40
	v_subrev_u32_e32 v152, s70, v40
	s_cbranch_vccnz .LBB0_549
	v_lshlrev_b64 v[32:33], 12, v[152:153]
	v_lshl_add_u64 v[32:33], s[28:29], 0, v[32:33]
	v_cndmask_b32_e64 v33, v33, v43, s[8:9]
	v_cndmask_b32_e64 v32, v32, v42, s[8:9]
	v_lshl_add_u64 v[36:37], v[170:171], 2, v[32:33]
	s_waitcnt vmcnt(10)
	v_mov_b32_e32 v32, v198
	v_mov_b32_e32 v33, v199
	v_mov_b32_e32 v34, v200
	v_mov_b32_e32 v35, v201
	v_mov_b32_e32 v36, v202
	v_mov_b32_e32 v37, v203
	v_mov_b32_e32 v38, v204
	v_mov_b32_e32 v39, v205
	s_mov_b64 s[8:9], 0
	s_branch .LBB0_550

.LBB0_552:
	v_pk_add_f32 v[30:31], v[30:31], v[70:71]
	v_pk_add_f32 v[28:29], v[28:29], v[68:69]
	v_pk_add_f32 v[26:27], v[26:27], v[66:67]
	v_pk_add_f32 v[24:25], v[24:25], v[64:65]
	v_pk_add_f32 v[38:39], v[30:31], v[38:39]
	v_pk_add_f32 v[36:37], v[28:29], v[36:37]
	v_pk_add_f32 v[34:35], v[26:27], v[34:35]
	v_pk_add_f32 v[46:47], v[24:25], v[32:33]
	v_cvt_pk_bf16_f32 v24, v36, v37
	v_cvt_pk_bf16_f32 v25, v38, v39
	v_cvt_pk_bf16_f32 v26, v46, v47
	v_cvt_pk_bf16_f32 v27, v34, v35
	s_and_b64 vcc, exec, s[6:7]
	global_store_dwordx4 v[48:49], v[24:27], off
	s_cbranch_vccnz .LBB0_559
	s_nop 0
	v_lshlrev_b64 v[24:25], 12, v[152:153]
	v_lshl_add_u64 v[24:25], s[28:29], 0, v[24:25]
	v_cmp_gt_i32_e32 vcc, s70, v40
	s_nop 1
	v_cndmask_b32_e32 v25, v25, v43, vcc
	v_cndmask_b32_e32 v24, v24, v42, vcc
	v_lshl_add_u64 v[28:29], v[144:145], 2, v[24:25]
	s_waitcnt vmcnt(8)
	v_mov_b32_e32 v24, v206
	v_mov_b32_e32 v25, v207
	v_mov_b32_e32 v26, v208
	v_mov_b32_e32 v27, v209
	v_mov_b32_e32 v28, v210
	v_mov_b32_e32 v29, v211
	v_mov_b32_e32 v30, v212
	v_mov_b32_e32 v31, v213
	v_lshl_add_u64 v[32:33], v[144:145], 1, v[44:45]
	s_cbranch_execnz .LBB0_555

.LBB0_557:
	s_or_b64 exec, exec, s[8:9]
	v_add_u32_e32 v24, 0xb0, v172
	v_ashrrev_i32_e32 v25, 31, v24
	s_waitcnt lgkmcnt(0)
	v_lshlrev_b64 v[16:17], 12, v[24:25]
	s_and_b64 vcc, exec, s[6:7]
	v_lshl_add_u64 v[26:27], s[48:49], 0, v[16:17]
	v_cmp_gt_i32_e64 s[8:9], s70, v24
	v_subrev_u32_e32 v152, s70, v24
	s_cbranch_vccnz .LBB0_560
	v_lshlrev_b64 v[16:17], 12, v[152:153]
	v_lshl_add_u64 v[16:17], s[28:29], 0, v[16:17]
	v_cndmask_b32_e64 v17, v17, v27, s[8:9]
	v_cndmask_b32_e64 v16, v16, v26, s[8:9]
	v_lshl_add_u64 v[20:21], v[170:171], 2, v[16:17]
	s_waitcnt vmcnt(6)
	v_mov_b32_e32 v16, v214
	v_mov_b32_e32 v17, v215
	v_mov_b32_e32 v18, v216
	v_mov_b32_e32 v19, v217
	v_mov_b32_e32 v20, v218
	v_mov_b32_e32 v21, v219
	v_mov_b32_e32 v22, v220
	v_mov_b32_e32 v23, v221
	s_mov_b64 s[8:9], 0
	s_branch .LBB0_561

.LBB0_563:
	v_pk_add_f32 v[14:15], v[14:15], v[70:71]
	v_pk_add_f32 v[12:13], v[12:13], v[68:69]
	v_pk_add_f32 v[10:11], v[10:11], v[66:67]
	v_pk_add_f32 v[8:9], v[8:9], v[64:65]
	v_pk_add_f32 v[22:23], v[14:15], v[22:23]
	v_pk_add_f32 v[20:21], v[12:13], v[20:21]
	v_pk_add_f32 v[18:19], v[10:11], v[18:19]
	v_pk_add_f32 v[30:31], v[8:9], v[16:17]
	v_cvt_pk_bf16_f32 v8, v20, v21
	v_cvt_pk_bf16_f32 v9, v22, v23
	v_cvt_pk_bf16_f32 v10, v30, v31
	v_cvt_pk_bf16_f32 v11, v18, v19
	s_and_b64 vcc, exec, s[6:7]
	global_store_dwordx4 v[32:33], v[8:11], off
	s_cbranch_vccnz .LBB0_571
	s_nop 0
	v_lshlrev_b64 v[8:9], 12, v[152:153]
	v_lshl_add_u64 v[8:9], s[28:29], 0, v[8:9]
	v_cmp_gt_i32_e32 vcc, s70, v24
	s_nop 1
	v_cndmask_b32_e32 v9, v9, v27, vcc
	v_cndmask_b32_e32 v8, v8, v26, vcc
	v_lshl_add_u64 v[12:13], v[144:145], 2, v[8:9]
	s_waitcnt vmcnt(4)
	v_mov_b32_e32 v8, v222
	v_mov_b32_e32 v9, v223
	v_mov_b32_e32 v10, v224
	v_mov_b32_e32 v11, v225
	v_mov_b32_e32 v12, v238
	v_mov_b32_e32 v13, v239
	v_mov_b32_e32 v14, v240
	v_mov_b32_e32 v15, v241
	v_lshl_add_u64 v[16:17], v[144:145], 1, v[28:29]
	s_cbranch_execnz .LBB0_566
